# baseline (speedup 1.0000x reference)
; #define LAS __attribute__((address_space(3)))
; DI void attn_sample_unit(const Args& a, int b, int g, LAS unsigned char* lds, const int tid) {
;     const bf16_t* HIN = (const bf16_t*)(a.ws + WS_HIN); bf16_t* MIX = (bf16_t*)(a.ws + WS_MIX);
;     const float* rc = (const float*)(a.ws + WS_ROPE); const float* rsn = rc + 2064 * 32;
;     LAS float* Kf = (LAS float*)lds; LAS float* Vf = Kf + 144 * 65; LAS float* Qf = Vf + 144 * 65; LAS float* Pf = Qf + 64 * 65;
;     const float* ck = a.in[4]; const float* cv = a.in[5];
;     for (int it = tid; it < 128 * 64; it += NTHR) { const int kr = it >> 6, d = it & 63; const size_t off = (((size_t)b * 128 + kr) * 2 + g) * 64 + d; Kf[kr * 65 + d] = ck[off]; Vf[kr * 65 + d] = cv[off]; }
.LBB0_116:
	v_mov_b32_e32 v132, v213
	s_cmpk_gt_i32 s16, 0x1ff
	s_mov_b64 s[0:1], -1
	s_cbranch_scc0 .LBB0_243
	s_cmpk_gt_u32 s16, 0x3ff
	s_cbranch_scc0 .LBB0_164
	s_cmpk_gt_u32 s16, 0xbff
	s_cbranch_scc0 .LBB0_143
	s_add_i32 s0, s16, 0xfffff400
	s_lshr_b32 s10, s0, 1
	s_movk_i32 s0, 0x2000
	s_and_b32 s11, s16, 1
	v_cmp_gt_i32_e32 vcc, s0, v132
	s_and_saveexec_b64 s[0:1], vcc
	v_readlane_b32 s56, v253, 27
	v_readlane_b32 s64, v253, 35
	v_readlane_b32 s65, v253, 36
	v_readlane_b32 s66, v253, 37
	v_readlane_b32 s67, v253, 38
	v_readlane_b32 s57, v253, 28
	v_readlane_b32 s58, v253, 29
	v_readlane_b32 s59, v253, 30
	v_readlane_b32 s60, v253, 31
	v_readlane_b32 s61, v253, 32
	v_readlane_b32 s62, v253, 33
	v_readlane_b32 s63, v253, 34
	v_readlane_b32 s68, v253, 39
	v_readlane_b32 s69, v253, 40
	v_readlane_b32 s70, v253, 41
	v_readlane_b32 s71, v253, 42
	s_cbranch_execz .LBB0_122
	v_and_b32_e32 v0, 63, v132
	s_lshl_b32 s94, s10, 7
	v_lshl_or_b32 v2, s11, 6, v0
	s_waitcnt lgkmcnt(0)
	v_ashrrev_i32_e32 v4, 6, v132
	v_add_u32_e32 v6, s94, v4
	v_lshlrev_b32_e32 v6, 9, v6
	v_lshl_or_b32 v6, v2, 2, v6
	s_movk_i32 s4, 0x41
	v_mad_u32_u24 v8, v4, s4, v0
	v_lshlrev_b32_e32 v8, 2, v8
	v_add_u32_e32 v9, 0x9240, v8
	global_load_dword v16, v6, s[64:65]
	global_load_dword v32, v6, s[66:67]
	v_add_u32_e32 v6, 0x1000, v6
	global_load_dword v17, v6, s[64:65]
	global_load_dword v33, v6, s[66:67]
	v_add_u32_e32 v6, 0x1000, v6
	global_load_dword v18, v6, s[64:65]
	global_load_dword v34, v6, s[66:67]
	v_add_u32_e32 v6, 0x1000, v6
	global_load_dword v19, v6, s[64:65]
	global_load_dword v35, v6, s[66:67]
	v_add_u32_e32 v6, 0x1000, v6
	global_load_dword v20, v6, s[64:65]
	global_load_dword v36, v6, s[66:67]
	v_add_u32_e32 v6, 0x1000, v6
	global_load_dword v21, v6, s[64:65]
	global_load_dword v37, v6, s[66:67]
	v_add_u32_e32 v6, 0x1000, v6
	global_load_dword v22, v6, s[64:65]
	global_load_dword v38, v6, s[66:67]
	v_add_u32_e32 v6, 0x1000, v6
	global_load_dword v23, v6, s[64:65]
	global_load_dword v39, v6, s[66:67]
	v_add_u32_e32 v6, 0x1000, v6
	global_load_dword v24, v6, s[64:65]
	global_load_dword v40, v6, s[66:67]
	v_add_u32_e32 v6, 0x1000, v6
	global_load_dword v25, v6, s[64:65]
	global_load_dword v41, v6, s[66:67]
	v_add_u32_e32 v6, 0x1000, v6
	global_load_dword v26, v6, s[64:65]
	global_load_dword v42, v6, s[66:67]
	v_add_u32_e32 v6, 0x1000, v6
	global_load_dword v27, v6, s[64:65]
	global_load_dword v43, v6, s[66:67]
	v_add_u32_e32 v6, 0x1000, v6
	global_load_dword v28, v6, s[64:65]
	global_load_dword v44, v6, s[66:67]
	v_add_u32_e32 v6, 0x1000, v6
	global_load_dword v29, v6, s[64:65]
	global_load_dword v45, v6, s[66:67]
	v_add_u32_e32 v6, 0x1000, v6
	global_load_dword v30, v6, s[64:65]
	global_load_dword v46, v6, s[66:67]
	v_add_u32_e32 v6, 0x1000, v6
	global_load_dword v31, v6, s[64:65]
	global_load_dword v47, v6, s[66:67]
	s_waitcnt vmcnt(16)
	ds_write_b32 v8, v16
	ds_write_b32 v9, v32
	ds_write_b32 v8, v17 offset:2080
	ds_write_b32 v9, v33 offset:2080
	ds_write_b32 v8, v18 offset:4160
	ds_write_b32 v9, v34 offset:4160
	ds_write_b32 v8, v19 offset:6240
	ds_write_b32 v9, v35 offset:6240
	ds_write_b32 v8, v20 offset:8320
	ds_write_b32 v9, v36 offset:8320
	ds_write_b32 v8, v21 offset:10400
	ds_write_b32 v9, v37 offset:10400
	ds_write_b32 v8, v22 offset:12480
	ds_write_b32 v9, v38 offset:12480
	ds_write_b32 v8, v23 offset:14560
	ds_write_b32 v9, v39 offset:14560
	s_waitcnt vmcnt(0)
	ds_write_b32 v8, v24 offset:16640
	ds_write_b32 v9, v40 offset:16640
	ds_write_b32 v8, v25 offset:18720
	ds_write_b32 v9, v41 offset:18720
	ds_write_b32 v8, v26 offset:20800
	ds_write_b32 v9, v42 offset:20800
	ds_write_b32 v8, v27 offset:22880
	ds_write_b32 v9, v43 offset:22880
	ds_write_b32 v8, v28 offset:24960
	ds_write_b32 v9, v44 offset:24960
	ds_write_b32 v8, v29 offset:27040
	ds_write_b32 v9, v45 offset:27040
	ds_write_b32 v8, v30 offset:29120
	ds_write_b32 v9, v46 offset:29120
	ds_write_b32 v8, v31 offset:31200
	ds_write_b32 v9, v47 offset:31200
